# lean epilogues for in-proj/gate, up and gated-merge GEMMs with interleaved exact rstd chains; rstd partial loads kept at epilogue entry (no pre-K-loop prefetch)
# baseline (speedup 1.0000x reference)
; DI int lane_id_opaque() { int l; asm volatile("v_mbcnt_lo_u32_b32 %0, -1, 0\n\tv_mbcnt_hi_u32_b32 %0, -1, %0" : "=v"(l)); return l; }
;     DI void operator()(AccRef acc, const pg8::Unit& u, int wr, int wc, int, int) const {
;         const int lane_ = lane_id_opaque(), fr = lane_ & 15, fq = lane_ >> 4;
;         EPI_PRELOAD_RSTD(ssq)
.Llean_C_entry:
	v_mbcnt_lo_u32_b32 v128, -1, 0
	v_mbcnt_hi_u32_b32 v128, -1, v128
	v_and_b32_e32 v129, 15, v128
	v_lshrrev_b32_e32 v130, 4, v128
	v_or_b32_e32 v129, s49, v129
	v_lshl_add_u32 v131, s88, 8, v129
	v_lshlrev_b32_e32 v132, 4, v130
	v_lshl_add_u32 v132, v131, 6, v132
	v_mov_b32_e32 v133, 0
	v_lshl_add_u64 v[134:135], s[60:61], 0, v[132:133]
	v_add_u32_e32 v132, 0x2000, v132
	v_lshl_add_u64 v[136:137], s[60:61], 0, v[132:133]
	global_load_dwordx4 v[140:143], v[134:135], off
	global_load_dwordx4 v[144:147], v[134:135], off offset:1024
	global_load_dwordx4 v[148:151], v[134:135], off offset:2048
	global_load_dwordx4 v[152:155], v[134:135], off offset:3072
	global_load_dwordx4 v[166:169], v[136:137], off
	global_load_dwordx4 v[170:173], v[136:137], off offset:1024
	global_load_dwordx4 v[174:177], v[136:137], off offset:2048
	global_load_dwordx4 v[178:181], v[136:137], off offset:3072
	v_readlane_b32 s4, v253, 51
	v_readlane_b32 s5, v253, 52
	v_mul_lo_u32 v236, v131, s43
	v_mov_b32_e32 v237, 0
	s_lshl_b32 s2, s80, 8
	s_or_b32 s2, s2, s62
	v_lshl_add_u32 v196, v130, 3, s2
	v_lshlrev_b32_e32 v196, 1, v196
	v_mov_b32_e32 v197, 0
	v_lshl_add_u64 v[236:237], v[236:237], 0, s[4:5]
	v_lshl_add_u64 v[236:237], v[236:237], 0, v[196:197]
	s_mov_b32 s2, 0x20800
	s_mov_b32 s3, 0
	s_mov_b32 s30, 0xa2800
	s_mov_b32 s31, 0
	v_mov_b32_e32 v195, 0x260
	s_waitcnt vmcnt(0)
	v_add_f32_e32 v208, v140, v141
	v_add_f32_e32 v209, v142, v143
	v_add_f32_e32 v208, v208, v209
	v_add_f32_e32 v210, v144, v145
	v_add_f32_e32 v211, v146, v147
	v_add_f32_e32 v210, v210, v211
	v_add_f32_e32 v212, v148, v149
	v_add_f32_e32 v213, v150, v151
	v_add_f32_e32 v212, v212, v213
	v_add_f32_e32 v214, v152, v153
	v_add_f32_e32 v215, v154, v155
	v_add_f32_e32 v214, v214, v215
	v_add_f32_e32 v216, v166, v167
	v_add_f32_e32 v217, v168, v169
	v_add_f32_e32 v216, v216, v217
	v_add_f32_e32 v218, v170, v171
	v_add_f32_e32 v219, v172, v173
	v_add_f32_e32 v218, v218, v219
	v_add_f32_e32 v184, v174, v175
	v_add_f32_e32 v185, v176, v177
	v_add_f32_e32 v184, v184, v185
	v_add_f32_e32 v186, v178, v179
	v_add_f32_e32 v187, v180, v181
	v_add_f32_e32 v186, v186, v187
	ds_swizzle_b32 v209, v208 offset:swizzle(SWAP,16)
	ds_swizzle_b32 v211, v210 offset:swizzle(SWAP,16)
	ds_swizzle_b32 v213, v212 offset:swizzle(SWAP,16)
	ds_swizzle_b32 v215, v214 offset:swizzle(SWAP,16)
	ds_swizzle_b32 v217, v216 offset:swizzle(SWAP,16)
	ds_swizzle_b32 v219, v218 offset:swizzle(SWAP,16)
	ds_swizzle_b32 v185, v184 offset:swizzle(SWAP,16)
	ds_swizzle_b32 v187, v186 offset:swizzle(SWAP,16)
	s_waitcnt lgkmcnt(0)
	v_add_f32_e32 v208, v208, v209
	v_add_f32_e32 v210, v210, v211
	v_add_f32_e32 v212, v212, v213
	v_add_f32_e32 v214, v214, v215
	v_add_f32_e32 v216, v216, v217
	v_add_f32_e32 v218, v218, v219
	v_add_f32_e32 v184, v184, v185
	v_add_f32_e32 v186, v186, v187
	v_mov_b32_e32 v209, v208
	v_mov_b32_e32 v211, v210
	v_mov_b32_e32 v213, v212
	v_mov_b32_e32 v215, v214
	v_mov_b32_e32 v217, v216
	v_mov_b32_e32 v219, v218
	v_mov_b32_e32 v185, v184
	v_mov_b32_e32 v187, v186
	s_nop 1
	v_permlane32_swap_b32_e32 v208, v209
	v_permlane32_swap_b32_e32 v210, v211
	v_permlane32_swap_b32_e32 v212, v213
	v_permlane32_swap_b32_e32 v214, v215
	v_permlane32_swap_b32_e32 v216, v217
	v_permlane32_swap_b32_e32 v218, v219
	v_permlane32_swap_b32_e32 v184, v185
	v_permlane32_swap_b32_e32 v186, v187
	v_add_f32_e32 v208, v208, v209
	v_add_f32_e32 v210, v210, v211
	v_add_f32_e32 v212, v212, v213
	v_add_f32_e32 v214, v214, v215
	v_add_f32_e32 v216, v216, v217
	v_add_f32_e32 v218, v218, v219
	v_add_f32_e32 v184, v184, v185
	v_add_f32_e32 v186, v186, v187
	v_fmamk_f32 v208, v208, 0x3a800000, v246
	v_fmamk_f32 v210, v210, 0x3a800000, v246
	v_sqrt_f32_e32 v188, v208
	v_sqrt_f32_e32 v140, v210
	v_add_u32_e32 v189, -1, v188
	v_add_u32_e32 v141, -1, v140
	v_fma_f32 v190, -v189, v188, v208
	v_fma_f32 v142, -v141, v140, v210
	v_cmp_ge_f32_e64 s[98:99], 0, v190
	v_cmp_ge_f32_e64 s[4:5], 0, v142
	v_add_u32_e32 v190, 1, v188
	v_add_u32_e32 v142, 1, v140
	v_cndmask_b32_e64 v189, v188, v189, s[98:99]
	v_cndmask_b32_e64 v141, v140, v141, s[4:5]
	v_fma_f32 v191, -v190, v188, v208
	v_fma_f32 v143, -v142, v140, v210
	v_cmp_lt_f32_e64 s[98:99], 0, v191
	v_cmp_lt_f32_e64 s[4:5], 0, v143
	s_nop 0
	v_cndmask_b32_e64 v188, v189, v190, s[98:99]
	v_cndmask_b32_e64 v140, v141, v142, s[4:5]
	v_rcp_f32_e32 v189, v188
	v_rcp_f32_e32 v141, v140
	v_fma_f32 v190, -v188, v189, 1.0
	v_fma_f32 v142, -v140, v141, 1.0
	v_fmac_f32_e32 v189, v190, v189
	v_fmac_f32_e32 v141, v142, v141
	v_fma_f32 v194, -v188, v189, 1.0
	v_fma_f32 v144, -v140, v141, 1.0
	v_fma_f32 v191, v194, v189, v189
	v_fma_f32 v143, v144, v141, v141
	v_fma_f32 v194, -v188, v191, 1.0
	v_fma_f32 v144, -v140, v143, 1.0
	v_fma_f32 v208, v194, v189, v191
	v_fma_f32 v210, v144, v141, v143
	v_fmamk_f32 v212, v212, 0x3a800000, v246
	v_fmamk_f32 v214, v214, 0x3a800000, v246
	v_sqrt_f32_e32 v188, v212
	v_sqrt_f32_e32 v140, v214
	v_add_u32_e32 v189, -1, v188
	v_add_u32_e32 v141, -1, v140
	v_fma_f32 v190, -v189, v188, v212
	v_fma_f32 v142, -v141, v140, v214
	v_cmp_ge_f32_e64 s[98:99], 0, v190
	v_cmp_ge_f32_e64 s[4:5], 0, v142
	v_add_u32_e32 v190, 1, v188
	v_add_u32_e32 v142, 1, v140
	v_cndmask_b32_e64 v189, v188, v189, s[98:99]
	v_cndmask_b32_e64 v141, v140, v141, s[4:5]
	v_fma_f32 v191, -v190, v188, v212
	v_fma_f32 v143, -v142, v140, v214
	v_cmp_lt_f32_e64 s[98:99], 0, v191
	v_cmp_lt_f32_e64 s[4:5], 0, v143
	s_nop 0
	v_cndmask_b32_e64 v188, v189, v190, s[98:99]
	v_cndmask_b32_e64 v140, v141, v142, s[4:5]
	v_rcp_f32_e32 v189, v188
	v_rcp_f32_e32 v141, v140
	v_fma_f32 v190, -v188, v189, 1.0
	v_fma_f32 v142, -v140, v141, 1.0
; __device__ __forceinline__ unsigned cvt_pk_bf16(float lo, float hi) { unsigned r; asm volatile("v_cvt_pk_bf16_f32 %0, %1, %2" : "=v"(r) : "v"(lo), "v"(hi)); return r; }
; #define GAS __attribute__((address_space(1)))
;     DI void operator()(AccRef acc, const pg8::Unit& u, int wr, int wc, int, int) const {
;     ...
;             const float rs = rs8[ai * 4 + m];
;             EPI_COLS_BEGIN
;                 {
;                     const f32x4 z4 = {0.f, 0.f, 0.f, 0.f}; const float rs2 = rs * rs;
;                     const f32x4 m0 = __builtin_elementwise_max(v0, z4), m1 = __builtin_elementwise_max(v1, z4);
;                     v0 = (v0 * m0) * rs2; v1 = (v1 * m1) * rs2;
;                 }
;                 u32x4 w; w.x = cvt_pk_bf16(v0[0], v0[1]); w.y = cvt_pk_bf16(v0[2], v0[3]); w.z = cvt_pk_bf16(v1[0], v1[1]); w.w = cvt_pk_bf16(v1[2], v1[3]);
;                 *(GAS u32x4*)(U + (size_t)lrow * UP + col) = w;
	v_fmac_f32_e32 v189, v190, v189
	v_fmac_f32_e32 v141, v142, v141
	v_fma_f32 v194, -v188, v189, 1.0
	v_fma_f32 v144, -v140, v141, 1.0
	v_fma_f32 v191, v194, v189, v189
	v_fma_f32 v143, v144, v141, v141
	v_fma_f32 v194, -v188, v191, 1.0
	v_fma_f32 v144, -v140, v143, 1.0
	v_fma_f32 v212, v194, v189, v191
	v_fma_f32 v214, v144, v141, v143
	v_fmamk_f32 v216, v216, 0x3a800000, v246
	v_fmamk_f32 v218, v218, 0x3a800000, v246
	v_sqrt_f32_e32 v188, v216
	v_sqrt_f32_e32 v140, v218
	v_add_u32_e32 v189, -1, v188
	v_add_u32_e32 v141, -1, v140
	v_fma_f32 v190, -v189, v188, v216
	v_fma_f32 v142, -v141, v140, v218
	v_cmp_ge_f32_e64 s[98:99], 0, v190
	v_cmp_ge_f32_e64 s[4:5], 0, v142
	v_add_u32_e32 v190, 1, v188
	v_add_u32_e32 v142, 1, v140
	v_cndmask_b32_e64 v189, v188, v189, s[98:99]
	v_cndmask_b32_e64 v141, v140, v141, s[4:5]
	v_fma_f32 v191, -v190, v188, v216
	v_fma_f32 v143, -v142, v140, v218
	v_cmp_lt_f32_e64 s[98:99], 0, v191
	v_cmp_lt_f32_e64 s[4:5], 0, v143
	s_nop 0
	v_cndmask_b32_e64 v188, v189, v190, s[98:99]
	v_cndmask_b32_e64 v140, v141, v142, s[4:5]
	v_rcp_f32_e32 v189, v188
	v_rcp_f32_e32 v141, v140
	v_fma_f32 v190, -v188, v189, 1.0
	v_fma_f32 v142, -v140, v141, 1.0
	v_fmac_f32_e32 v189, v190, v189
	v_fmac_f32_e32 v141, v142, v141
	v_fma_f32 v194, -v188, v189, 1.0
	v_fma_f32 v144, -v140, v141, 1.0
	v_fma_f32 v191, v194, v189, v189
	v_fma_f32 v143, v144, v141, v141
	v_fma_f32 v194, -v188, v191, 1.0
	v_fma_f32 v144, -v140, v143, 1.0
	v_fma_f32 v216, v194, v189, v191
	v_fma_f32 v218, v144, v141, v143
	v_fmamk_f32 v184, v184, 0x3a800000, v246
	v_fmamk_f32 v186, v186, 0x3a800000, v246
	v_sqrt_f32_e32 v188, v184
	v_sqrt_f32_e32 v140, v186
	v_add_u32_e32 v189, -1, v188
	v_add_u32_e32 v141, -1, v140
	v_fma_f32 v190, -v189, v188, v184
	v_fma_f32 v142, -v141, v140, v186
	v_cmp_ge_f32_e64 s[98:99], 0, v190
	v_cmp_ge_f32_e64 s[4:5], 0, v142
	v_add_u32_e32 v190, 1, v188
	v_add_u32_e32 v142, 1, v140
	v_cndmask_b32_e64 v189, v188, v189, s[98:99]
	v_cndmask_b32_e64 v141, v140, v141, s[4:5]
	v_fma_f32 v191, -v190, v188, v184
	v_fma_f32 v143, -v142, v140, v186
	v_cmp_lt_f32_e64 s[98:99], 0, v191
	v_cmp_lt_f32_e64 s[4:5], 0, v143
	s_nop 0
	v_cndmask_b32_e64 v188, v189, v190, s[98:99]
	v_cndmask_b32_e64 v140, v141, v142, s[4:5]
	v_rcp_f32_e32 v189, v188
	v_rcp_f32_e32 v141, v140
	v_fma_f32 v190, -v188, v189, 1.0
	v_fma_f32 v142, -v140, v141, 1.0
	v_fmac_f32_e32 v189, v190, v189
	v_fmac_f32_e32 v141, v142, v141
	v_fma_f32 v194, -v188, v189, 1.0
	v_fma_f32 v144, -v140, v141, 1.0
	v_fma_f32 v191, v194, v189, v189
	v_fma_f32 v143, v144, v141, v141
	v_fma_f32 v194, -v188, v191, 1.0
	v_fma_f32 v144, -v140, v143, 1.0
	v_fma_f32 v184, v194, v189, v191
	v_fma_f32 v186, v144, v141, v143
	v_mul_f32_e32 v208, v208, v208
	v_mul_f32_e32 v210, v210, v210
	v_mul_f32_e32 v212, v212, v212
	v_mul_f32_e32 v214, v214, v214
	v_mul_f32_e32 v216, v216, v216
	v_mul_f32_e32 v218, v218, v218
	v_mul_f32_e32 v184, v184, v184
	v_mul_f32_e32 v186, v186, v186
	v_max_f32_e32 v140, 0, v124
	v_max_f32_e32 v141, 0, v125
	v_max_f32_e32 v142, 0, v126
	v_max_f32_e32 v143, 0, v127
	v_max_f32_e32 v144, 0, v120
	v_max_f32_e32 v145, 0, v121
	v_max_f32_e32 v146, 0, v122
	v_max_f32_e32 v147, 0, v123
	v_pk_mul_f32 v[124:125], v[124:125], v[140:141]
	v_pk_mul_f32 v[126:127], v[126:127], v[142:143]
	v_pk_mul_f32 v[120:121], v[120:121], v[144:145]
	v_pk_mul_f32 v[122:123], v[122:123], v[146:147]
	v_pk_mul_f32 v[124:125], v[124:125], v[208:209] op_sel_hi:[1,0]
	v_pk_mul_f32 v[126:127], v[126:127], v[208:209] op_sel_hi:[1,0]
	v_pk_mul_f32 v[120:121], v[120:121], v[208:209] op_sel_hi:[1,0]
	v_pk_mul_f32 v[122:123], v[122:123], v[208:209] op_sel_hi:[1,0]
	v_cvt_pk_bf16_f32 v220, v124, v125
	v_cvt_pk_bf16_f32 v221, v126, v127
	v_cvt_pk_bf16_f32 v222, v120, v121
	v_cvt_pk_bf16_f32 v223, v122, v123
	global_store_dwordx4 v[236:237], v[220:223], off
	v_max_f32_e32 v140, 0, v116
	v_max_f32_e32 v141, 0, v117
	v_max_f32_e32 v142, 0, v118
	v_max_f32_e32 v143, 0, v119
	v_max_f32_e32 v144, 0, v112
	v_max_f32_e32 v145, 0, v113
	v_max_f32_e32 v146, 0, v114
	v_max_f32_e32 v147, 0, v115
	v_pk_mul_f32 v[116:117], v[116:117], v[140:141]
	v_pk_mul_f32 v[118:119], v[118:119], v[142:143]
	v_pk_mul_f32 v[112:113], v[112:113], v[144:145]
	v_pk_mul_f32 v[114:115], v[114:115], v[146:147]
	v_pk_mul_f32 v[116:117], v[116:117], v[208:209] op_sel_hi:[1,0]
	v_pk_mul_f32 v[118:119], v[118:119], v[208:209] op_sel_hi:[1,0]
	v_pk_mul_f32 v[112:113], v[112:113], v[208:209] op_sel_hi:[1,0]
	v_pk_mul_f32 v[114:115], v[114:115], v[208:209] op_sel_hi:[1,0]
	v_cvt_pk_bf16_f32 v224, v116, v117
	v_cvt_pk_bf16_f32 v225, v118, v119
	v_cvt_pk_bf16_f32 v226, v112, v113
	v_cvt_pk_bf16_f32 v227, v114, v115
	global_store_dwordx4 v[236:237], v[224:227], off offset:256
	v_lshl_add_u64 v[238:239], v[236:237], 0, s[2:3]
	v_max_f32_e32 v140, 0, v108
	v_max_f32_e32 v141, 0, v109
	v_max_f32_e32 v142, 0, v110
	v_max_f32_e32 v143, 0, v111
	v_max_f32_e32 v144, 0, v104
	v_max_f32_e32 v145, 0, v105
	v_max_f32_e32 v146, 0, v106
	v_max_f32_e32 v147, 0, v107
	v_pk_mul_f32 v[108:109], v[108:109], v[140:141]
	v_pk_mul_f32 v[110:111], v[110:111], v[142:143]
	v_pk_mul_f32 v[104:105], v[104:105], v[144:145]
	v_pk_mul_f32 v[106:107], v[106:107], v[146:147]
	v_pk_mul_f32 v[108:109], v[108:109], v[210:211] op_sel_hi:[1,0]
	v_pk_mul_f32 v[110:111], v[110:111], v[210:211] op_sel_hi:[1,0]
	v_pk_mul_f32 v[104:105], v[104:105], v[210:211] op_sel_hi:[1,0]
	v_pk_mul_f32 v[106:107], v[106:107], v[210:211] op_sel_hi:[1,0]
	v_cvt_pk_bf16_f32 v228, v108, v109
	v_cvt_pk_bf16_f32 v229, v110, v111
	v_cvt_pk_bf16_f32 v230, v104, v105
	v_cvt_pk_bf16_f32 v231, v106, v107
; __device__ __forceinline__ unsigned cvt_pk_bf16(float lo, float hi) { unsigned r; asm volatile("v_cvt_pk_bf16_f32 %0, %1, %2" : "=v"(r) : "v"(lo), "v"(hi)); return r; }
; #define GAS __attribute__((address_space(1)))
;     DI void operator()(AccRef acc, const pg8::Unit& u, int wr, int wc, int, int) const {
;     ...
;             const float rs = rs8[ai * 4 + m];
;             EPI_COLS_BEGIN
;                 {
;                     const f32x4 z4 = {0.f, 0.f, 0.f, 0.f}; const float rs2 = rs * rs;
;                     const f32x4 m0 = __builtin_elementwise_max(v0, z4), m1 = __builtin_elementwise_max(v1, z4);
;                     v0 = (v0 * m0) * rs2; v1 = (v1 * m1) * rs2;
;                 }
;                 u32x4 w; w.x = cvt_pk_bf16(v0[0], v0[1]); w.y = cvt_pk_bf16(v0[2], v0[3]); w.z = cvt_pk_bf16(v1[0], v1[1]); w.w = cvt_pk_bf16(v1[2], v1[3]);
;                 *(GAS u32x4*)(U + (size_t)lrow * UP + col) = w;
	global_store_dwordx4 v[238:239], v[228:231], off
	v_max_f32_e32 v140, 0, v100
	v_max_f32_e32 v141, 0, v101
	v_max_f32_e32 v142, 0, v102
	v_max_f32_e32 v143, 0, v103
	v_max_f32_e32 v144, 0, v96
	v_max_f32_e32 v145, 0, v97
	v_max_f32_e32 v146, 0, v98
	v_max_f32_e32 v147, 0, v99
	v_pk_mul_f32 v[100:101], v[100:101], v[140:141]
	v_pk_mul_f32 v[102:103], v[102:103], v[142:143]
	v_pk_mul_f32 v[96:97], v[96:97], v[144:145]
	v_pk_mul_f32 v[98:99], v[98:99], v[146:147]
	v_pk_mul_f32 v[100:101], v[100:101], v[210:211] op_sel_hi:[1,0]
	v_pk_mul_f32 v[102:103], v[102:103], v[210:211] op_sel_hi:[1,0]
	v_pk_mul_f32 v[96:97], v[96:97], v[210:211] op_sel_hi:[1,0]
	v_pk_mul_f32 v[98:99], v[98:99], v[210:211] op_sel_hi:[1,0]
	v_cvt_pk_bf16_f32 v232, v100, v101
	v_cvt_pk_bf16_f32 v233, v102, v103
	v_cvt_pk_bf16_f32 v234, v96, v97
	v_cvt_pk_bf16_f32 v235, v98, v99
	global_store_dwordx4 v[238:239], v[232:235], off offset:256
	v_lshl_add_u64 v[236:237], v[238:239], 0, s[2:3]
	v_max_f32_e32 v140, 0, v92
	v_max_f32_e32 v141, 0, v93
	v_max_f32_e32 v142, 0, v94
	v_max_f32_e32 v143, 0, v95
	v_max_f32_e32 v144, 0, v88
	v_max_f32_e32 v145, 0, v89
	v_max_f32_e32 v146, 0, v90
	v_max_f32_e32 v147, 0, v91
	v_pk_mul_f32 v[92:93], v[92:93], v[140:141]
	v_pk_mul_f32 v[94:95], v[94:95], v[142:143]
	v_pk_mul_f32 v[88:89], v[88:89], v[144:145]
	v_pk_mul_f32 v[90:91], v[90:91], v[146:147]
	v_pk_mul_f32 v[92:93], v[92:93], v[212:213] op_sel_hi:[1,0]
	v_pk_mul_f32 v[94:95], v[94:95], v[212:213] op_sel_hi:[1,0]
	v_pk_mul_f32 v[88:89], v[88:89], v[212:213] op_sel_hi:[1,0]
	v_pk_mul_f32 v[90:91], v[90:91], v[212:213] op_sel_hi:[1,0]
	v_cvt_pk_bf16_f32 v220, v92, v93
	v_cvt_pk_bf16_f32 v221, v94, v95
	v_cvt_pk_bf16_f32 v222, v88, v89
	v_cvt_pk_bf16_f32 v223, v90, v91
	global_store_dwordx4 v[236:237], v[220:223], off
	v_max_f32_e32 v140, 0, v84
	v_max_f32_e32 v141, 0, v85
	v_max_f32_e32 v142, 0, v86
	v_max_f32_e32 v143, 0, v87
	v_max_f32_e32 v144, 0, v80
	v_max_f32_e32 v145, 0, v81
	v_max_f32_e32 v146, 0, v82
	v_max_f32_e32 v147, 0, v83
	v_pk_mul_f32 v[84:85], v[84:85], v[140:141]
	v_pk_mul_f32 v[86:87], v[86:87], v[142:143]
	v_pk_mul_f32 v[80:81], v[80:81], v[144:145]
	v_pk_mul_f32 v[82:83], v[82:83], v[146:147]
	v_pk_mul_f32 v[84:85], v[84:85], v[212:213] op_sel_hi:[1,0]
	v_pk_mul_f32 v[86:87], v[86:87], v[212:213] op_sel_hi:[1,0]
	v_pk_mul_f32 v[80:81], v[80:81], v[212:213] op_sel_hi:[1,0]
	v_pk_mul_f32 v[82:83], v[82:83], v[212:213] op_sel_hi:[1,0]
	v_cvt_pk_bf16_f32 v224, v84, v85
	v_cvt_pk_bf16_f32 v225, v86, v87
	v_cvt_pk_bf16_f32 v226, v80, v81
	v_cvt_pk_bf16_f32 v227, v82, v83
	global_store_dwordx4 v[236:237], v[224:227], off offset:256
	v_lshl_add_u64 v[238:239], v[236:237], 0, s[2:3]
	v_max_f32_e32 v140, 0, v76
	v_max_f32_e32 v141, 0, v77
	v_max_f32_e32 v142, 0, v78
	v_max_f32_e32 v143, 0, v79
	v_max_f32_e32 v144, 0, v72
	v_max_f32_e32 v145, 0, v73
	v_max_f32_e32 v146, 0, v74
	v_max_f32_e32 v147, 0, v75
	v_pk_mul_f32 v[76:77], v[76:77], v[140:141]
	v_pk_mul_f32 v[78:79], v[78:79], v[142:143]
	v_pk_mul_f32 v[72:73], v[72:73], v[144:145]
	v_pk_mul_f32 v[74:75], v[74:75], v[146:147]
	v_pk_mul_f32 v[76:77], v[76:77], v[214:215] op_sel_hi:[1,0]
	v_pk_mul_f32 v[78:79], v[78:79], v[214:215] op_sel_hi:[1,0]
	v_pk_mul_f32 v[72:73], v[72:73], v[214:215] op_sel_hi:[1,0]
	v_pk_mul_f32 v[74:75], v[74:75], v[214:215] op_sel_hi:[1,0]
	v_cvt_pk_bf16_f32 v228, v76, v77
	v_cvt_pk_bf16_f32 v229, v78, v79
	v_cvt_pk_bf16_f32 v230, v72, v73
	v_cvt_pk_bf16_f32 v231, v74, v75
	global_store_dwordx4 v[238:239], v[228:231], off
	v_max_f32_e32 v140, 0, v68
	v_max_f32_e32 v141, 0, v69
	v_max_f32_e32 v142, 0, v70
	v_max_f32_e32 v143, 0, v71
	v_max_f32_e32 v144, 0, v64
	v_max_f32_e32 v145, 0, v65
	v_max_f32_e32 v146, 0, v66
	v_max_f32_e32 v147, 0, v67
	v_pk_mul_f32 v[68:69], v[68:69], v[140:141]
	v_pk_mul_f32 v[70:71], v[70:71], v[142:143]
	v_pk_mul_f32 v[64:65], v[64:65], v[144:145]
	v_pk_mul_f32 v[66:67], v[66:67], v[146:147]
	v_pk_mul_f32 v[68:69], v[68:69], v[214:215] op_sel_hi:[1,0]
	v_pk_mul_f32 v[70:71], v[70:71], v[214:215] op_sel_hi:[1,0]
	v_pk_mul_f32 v[64:65], v[64:65], v[214:215] op_sel_hi:[1,0]
	v_pk_mul_f32 v[66:67], v[66:67], v[214:215] op_sel_hi:[1,0]
	v_cvt_pk_bf16_f32 v232, v68, v69
	v_cvt_pk_bf16_f32 v233, v70, v71
	v_cvt_pk_bf16_f32 v234, v64, v65
	v_cvt_pk_bf16_f32 v235, v66, v67
	global_store_dwordx4 v[238:239], v[232:235], off offset:256
	v_lshl_add_u64 v[236:237], v[238:239], 0, s[30:31]
	v_max_f32_e32 v140, 0, v60
	v_max_f32_e32 v141, 0, v61
	v_max_f32_e32 v142, 0, v62
	v_max_f32_e32 v143, 0, v63
	v_max_f32_e32 v144, 0, v56
	v_max_f32_e32 v145, 0, v57
	v_max_f32_e32 v146, 0, v58
	v_max_f32_e32 v147, 0, v59
	v_pk_mul_f32 v[60:61], v[60:61], v[140:141]
	v_pk_mul_f32 v[62:63], v[62:63], v[142:143]
	v_pk_mul_f32 v[56:57], v[56:57], v[144:145]
	v_pk_mul_f32 v[58:59], v[58:59], v[146:147]
	v_pk_mul_f32 v[60:61], v[60:61], v[216:217] op_sel_hi:[1,0]
	v_pk_mul_f32 v[62:63], v[62:63], v[216:217] op_sel_hi:[1,0]
	v_pk_mul_f32 v[56:57], v[56:57], v[216:217] op_sel_hi:[1,0]
	v_pk_mul_f32 v[58:59], v[58:59], v[216:217] op_sel_hi:[1,0]
	v_cvt_pk_bf16_f32 v220, v60, v61
	v_cvt_pk_bf16_f32 v221, v62, v63
	v_cvt_pk_bf16_f32 v222, v56, v57
	v_cvt_pk_bf16_f32 v223, v58, v59
	global_store_dwordx4 v[236:237], v[220:223], off
	v_max_f32_e32 v140, 0, v52
	v_max_f32_e32 v141, 0, v53
	v_max_f32_e32 v142, 0, v54
	v_max_f32_e32 v143, 0, v55
	v_max_f32_e32 v144, 0, v48
	v_max_f32_e32 v145, 0, v49
	v_max_f32_e32 v146, 0, v50
	v_max_f32_e32 v147, 0, v51
	v_pk_mul_f32 v[52:53], v[52:53], v[140:141]
	v_pk_mul_f32 v[54:55], v[54:55], v[142:143]
	v_pk_mul_f32 v[48:49], v[48:49], v[144:145]
; __device__ __forceinline__ unsigned cvt_pk_bf16(float lo, float hi) { unsigned r; asm volatile("v_cvt_pk_bf16_f32 %0, %1, %2" : "=v"(r) : "v"(lo), "v"(hi)); return r; }
; #define PG8_BAR __builtin_amdgcn_s_barrier()
; #define GAS __attribute__((address_space(1)))
; template <class Epi, class Sched, bool ALIGN_EPI = false, bool SP2 = false>
; __device__ __forceinline__ void gemm_phase(PG8_LAS unsigned char* lds, const Gemm g, const Sched& S, const Epi& E) {
;     ...
;         if constexpr (ALIGN_EPI) { if (wr == 0) PG8_BAR; }
;         if constexpr (!Epi::AFTER_DRAIN) { E(acc, cur, wr, wc, fr, fq); S.done(cur); }
;         if (!has_next) break;
;     DI void operator()(AccRef acc, const pg8::Unit& u, int wr, int wc, int, int) const {
;     ...
;                     const f32x4 z4 = {0.f, 0.f, 0.f, 0.f}; const float rs2 = rs * rs;
;                     const f32x4 m0 = __builtin_elementwise_max(v0, z4), m1 = __builtin_elementwise_max(v1, z4);
;                     v0 = (v0 * m0) * rs2; v1 = (v1 * m1) * rs2;
;                 }
;                 u32x4 w; w.x = cvt_pk_bf16(v0[0], v0[1]); w.y = cvt_pk_bf16(v0[2], v0[3]); w.z = cvt_pk_bf16(v1[0], v1[1]); w.w = cvt_pk_bf16(v1[2], v1[3]);
;                 *(GAS u32x4*)(U + (size_t)lrow * UP + col) = w;
	v_pk_mul_f32 v[50:51], v[50:51], v[146:147]
	v_pk_mul_f32 v[52:53], v[52:53], v[216:217] op_sel_hi:[1,0]
	v_pk_mul_f32 v[54:55], v[54:55], v[216:217] op_sel_hi:[1,0]
	v_pk_mul_f32 v[48:49], v[48:49], v[216:217] op_sel_hi:[1,0]
	v_pk_mul_f32 v[50:51], v[50:51], v[216:217] op_sel_hi:[1,0]
	v_cvt_pk_bf16_f32 v224, v52, v53
	v_cvt_pk_bf16_f32 v225, v54, v55
	v_cvt_pk_bf16_f32 v226, v48, v49
	v_cvt_pk_bf16_f32 v227, v50, v51
	global_store_dwordx4 v[236:237], v[224:227], off offset:256
	v_lshl_add_u64 v[238:239], v[236:237], 0, s[2:3]
	v_max_f32_e32 v140, 0, v44
	v_max_f32_e32 v141, 0, v45
	v_max_f32_e32 v142, 0, v46
	v_max_f32_e32 v143, 0, v47
	v_max_f32_e32 v144, 0, v40
	v_max_f32_e32 v145, 0, v41
	v_max_f32_e32 v146, 0, v42
	v_max_f32_e32 v147, 0, v43
	v_pk_mul_f32 v[44:45], v[44:45], v[140:141]
	v_pk_mul_f32 v[46:47], v[46:47], v[142:143]
	v_pk_mul_f32 v[40:41], v[40:41], v[144:145]
	v_pk_mul_f32 v[42:43], v[42:43], v[146:147]
	v_pk_mul_f32 v[44:45], v[44:45], v[218:219] op_sel_hi:[1,0]
	v_pk_mul_f32 v[46:47], v[46:47], v[218:219] op_sel_hi:[1,0]
	v_pk_mul_f32 v[40:41], v[40:41], v[218:219] op_sel_hi:[1,0]
	v_pk_mul_f32 v[42:43], v[42:43], v[218:219] op_sel_hi:[1,0]
	v_cvt_pk_bf16_f32 v228, v44, v45
	v_cvt_pk_bf16_f32 v229, v46, v47
	v_cvt_pk_bf16_f32 v230, v40, v41
	v_cvt_pk_bf16_f32 v231, v42, v43
	global_store_dwordx4 v[238:239], v[228:231], off
	v_max_f32_e32 v140, 0, v36
	v_max_f32_e32 v141, 0, v37
	v_max_f32_e32 v142, 0, v38
	v_max_f32_e32 v143, 0, v39
	v_max_f32_e32 v144, 0, v32
	v_max_f32_e32 v145, 0, v33
	v_max_f32_e32 v146, 0, v34
	v_max_f32_e32 v147, 0, v35
	v_pk_mul_f32 v[36:37], v[36:37], v[140:141]
	v_pk_mul_f32 v[38:39], v[38:39], v[142:143]
	v_pk_mul_f32 v[32:33], v[32:33], v[144:145]
	v_pk_mul_f32 v[34:35], v[34:35], v[146:147]
	v_pk_mul_f32 v[36:37], v[36:37], v[218:219] op_sel_hi:[1,0]
	v_pk_mul_f32 v[38:39], v[38:39], v[218:219] op_sel_hi:[1,0]
	v_pk_mul_f32 v[32:33], v[32:33], v[218:219] op_sel_hi:[1,0]
	v_pk_mul_f32 v[34:35], v[34:35], v[218:219] op_sel_hi:[1,0]
	v_cvt_pk_bf16_f32 v232, v36, v37
	v_cvt_pk_bf16_f32 v233, v38, v39
	v_cvt_pk_bf16_f32 v234, v32, v33
	v_cvt_pk_bf16_f32 v235, v34, v35
	global_store_dwordx4 v[238:239], v[232:235], off offset:256
	v_lshl_add_u64 v[236:237], v[238:239], 0, s[2:3]
	v_max_f32_e32 v140, 0, v28
	v_max_f32_e32 v141, 0, v29
	v_max_f32_e32 v142, 0, v30
	v_max_f32_e32 v143, 0, v31
	v_max_f32_e32 v144, 0, v24
	v_max_f32_e32 v145, 0, v25
	v_max_f32_e32 v146, 0, v26
	v_max_f32_e32 v147, 0, v27
	v_pk_mul_f32 v[28:29], v[28:29], v[140:141]
	v_pk_mul_f32 v[30:31], v[30:31], v[142:143]
	v_pk_mul_f32 v[24:25], v[24:25], v[144:145]
	v_pk_mul_f32 v[26:27], v[26:27], v[146:147]
	v_pk_mul_f32 v[28:29], v[28:29], v[184:185] op_sel_hi:[1,0]
	v_pk_mul_f32 v[30:31], v[30:31], v[184:185] op_sel_hi:[1,0]
	v_pk_mul_f32 v[24:25], v[24:25], v[184:185] op_sel_hi:[1,0]
	v_pk_mul_f32 v[26:27], v[26:27], v[184:185] op_sel_hi:[1,0]
	v_cvt_pk_bf16_f32 v220, v28, v29
	v_cvt_pk_bf16_f32 v221, v30, v31
	v_cvt_pk_bf16_f32 v222, v24, v25
	v_cvt_pk_bf16_f32 v223, v26, v27
	global_store_dwordx4 v[236:237], v[220:223], off
	v_max_f32_e32 v140, 0, v20
	v_max_f32_e32 v141, 0, v21
	v_max_f32_e32 v142, 0, v22
	v_max_f32_e32 v143, 0, v23
	v_max_f32_e32 v144, 0, v16
	v_max_f32_e32 v145, 0, v17
	v_max_f32_e32 v146, 0, v18
	v_max_f32_e32 v147, 0, v19
	v_pk_mul_f32 v[20:21], v[20:21], v[140:141]
	v_pk_mul_f32 v[22:23], v[22:23], v[142:143]
	v_pk_mul_f32 v[16:17], v[16:17], v[144:145]
	v_pk_mul_f32 v[18:19], v[18:19], v[146:147]
	v_pk_mul_f32 v[20:21], v[20:21], v[184:185] op_sel_hi:[1,0]
	v_pk_mul_f32 v[22:23], v[22:23], v[184:185] op_sel_hi:[1,0]
	v_pk_mul_f32 v[16:17], v[16:17], v[184:185] op_sel_hi:[1,0]
	v_pk_mul_f32 v[18:19], v[18:19], v[184:185] op_sel_hi:[1,0]
	v_cvt_pk_bf16_f32 v224, v20, v21
	v_cvt_pk_bf16_f32 v225, v22, v23
	v_cvt_pk_bf16_f32 v226, v16, v17
	v_cvt_pk_bf16_f32 v227, v18, v19
	global_store_dwordx4 v[236:237], v[224:227], off offset:256
	v_lshl_add_u64 v[238:239], v[236:237], 0, s[2:3]
	v_max_f32_e32 v140, 0, v12
	v_max_f32_e32 v141, 0, v13
	v_max_f32_e32 v142, 0, v14
	v_max_f32_e32 v143, 0, v15
	v_max_f32_e32 v144, 0, v8
	v_max_f32_e32 v145, 0, v9
	v_max_f32_e32 v146, 0, v10
	v_max_f32_e32 v147, 0, v11
	v_pk_mul_f32 v[12:13], v[12:13], v[140:141]
	v_pk_mul_f32 v[14:15], v[14:15], v[142:143]
	v_pk_mul_f32 v[8:9], v[8:9], v[144:145]
	v_pk_mul_f32 v[10:11], v[10:11], v[146:147]
	v_pk_mul_f32 v[12:13], v[12:13], v[186:187] op_sel_hi:[1,0]
	v_pk_mul_f32 v[14:15], v[14:15], v[186:187] op_sel_hi:[1,0]
	v_pk_mul_f32 v[8:9], v[8:9], v[186:187] op_sel_hi:[1,0]
	v_pk_mul_f32 v[10:11], v[10:11], v[186:187] op_sel_hi:[1,0]
	v_cvt_pk_bf16_f32 v228, v12, v13
	v_cvt_pk_bf16_f32 v229, v14, v15
	v_cvt_pk_bf16_f32 v230, v8, v9
	v_cvt_pk_bf16_f32 v231, v10, v11
	global_store_dwordx4 v[238:239], v[228:231], off
	v_max_f32_e32 v140, 0, v4
	v_max_f32_e32 v141, 0, v5
	v_max_f32_e32 v142, 0, v6
	v_max_f32_e32 v143, 0, v7
	v_max_f32_e32 v144, 0, v0
	v_max_f32_e32 v145, 0, v1
	v_max_f32_e32 v146, 0, v2
	v_max_f32_e32 v147, 0, v3
	v_pk_mul_f32 v[4:5], v[4:5], v[140:141]
	v_pk_mul_f32 v[6:7], v[6:7], v[142:143]
	v_pk_mul_f32 v[0:1], v[0:1], v[144:145]
	v_pk_mul_f32 v[2:3], v[2:3], v[146:147]
	v_pk_mul_f32 v[4:5], v[4:5], v[186:187] op_sel_hi:[1,0]
	v_pk_mul_f32 v[6:7], v[6:7], v[186:187] op_sel_hi:[1,0]
	v_pk_mul_f32 v[0:1], v[0:1], v[186:187] op_sel_hi:[1,0]
	v_pk_mul_f32 v[2:3], v[2:3], v[186:187] op_sel_hi:[1,0]
	v_cvt_pk_bf16_f32 v232, v4, v5
	v_cvt_pk_bf16_f32 v233, v6, v7
	v_cvt_pk_bf16_f32 v234, v0, v1
	v_cvt_pk_bf16_f32 v235, v2, v3
	global_store_dwordx4 v[238:239], v[232:235], off offset:256
	s_andn2_b64 vcc, exec, s[0:1]
	s_mov_b64 s[4:5], -1
	s_cbranch_vccnz .LBB0_685
	s_andn2_b64 vcc, exec, s[10:11]
	s_cbranch_vccnz .LBB0_684
	s_barrier
	s_branch .LBB0_684

; DI int lane_id_opaque() { int l; asm volatile("v_mbcnt_lo_u32_b32 %0, -1, 0\n\tv_mbcnt_hi_u32_b32 %0, -1, %0" : "=v"(l)); return l; }
;     DI void operator()(AccRef acc, const pg8::Unit& u, int wr, int wc, int, int) const {
;         const int lane_ = lane_id_opaque(), fr = lane_ & 15, fq = lane_ >> 4;
;         const int pn = u.pn;
;         const int kind = dummy ? 2 : (kind_force >= 0 ? kind_force : (pn < 6 ? (pn < 3 ? 0 : 1) : (pn < 15 ? 2 : (pn < 19 ? 3 : 4))));
;         const bool rot = (kind < 2) && ((wc & 1) == 0);
;         const float qs = (kind == 0) ? 0.125f : 1.0f;
;         EPI_PRELOAD_RSTD(ssq)
.Llean_F_entry:
	v_and_b32_e32 v136, 15, v226
	v_lshrrev_b32_e32 v137, 4, v226
	v_or_b32_e32 v136, s49, v136
	v_lshl_add_u32 v138, s6, 8, v136
	v_lshlrev_b32_e32 v140, 4, v137
	v_lshl_add_u32 v140, v138, 6, v140
	v_mov_b32_e32 v141, 0
	v_lshl_add_u64 v[142:143], s[26:27], 0, v[140:141]
	v_add_u32_e32 v140, 0x2000, v140
	v_lshl_add_u64 v[144:145], s[26:27], 0, v[140:141]
	global_load_dwordx4 v[72:75], v[142:143], off
	global_load_dwordx4 v[76:79], v[142:143], off offset:1024
	global_load_dwordx4 v[80:83], v[142:143], off offset:2048
	global_load_dwordx4 v[84:87], v[142:143], off offset:3072
	global_load_dwordx4 v[104:107], v[144:145], off
	global_load_dwordx4 v[108:111], v[144:145], off offset:1024
	global_load_dwordx4 v[112:115], v[144:145], off offset:2048
	global_load_dwordx4 v[116:119], v[144:145], off offset:3072
	v_mul_lo_u32 v146, v138, s39
	v_mov_b32_e32 v147, 0
	s_lshl_b32 s0, s14, 8
	s_add_i32 s0, s0, s20
	v_lshl_add_u32 v148, v137, 3, s0
	v_lshlrev_b32_e32 v148, 1, v148
	v_mov_b32_e32 v149, 0
	v_lshl_add_u64 v[146:147], v[146:147], 1, s[72:73]
	v_lshl_add_u64 v[146:147], v[146:147], 0, v[148:149]
	s_lshl_b32 s2, s39, 5
	s_mov_b32 s3, 0
	s_mul_i32 s0, s39, 0xa0
	s_mov_b32 s1, 0
	v_mov_b32_e32 v213, 0x260
	s_waitcnt vmcnt(0)
	v_add_f32_e32 v168, v72, v73
	v_add_f32_e32 v169, v74, v75
	v_add_f32_e32 v168, v168, v169
	v_add_f32_e32 v170, v76, v77
	v_add_f32_e32 v171, v78, v79
	v_add_f32_e32 v170, v170, v171
	v_add_f32_e32 v172, v80, v81
	v_add_f32_e32 v173, v82, v83
	v_add_f32_e32 v172, v172, v173
	v_add_f32_e32 v174, v84, v85
	v_add_f32_e32 v175, v86, v87
	v_add_f32_e32 v174, v174, v175
	v_add_f32_e32 v176, v104, v105
	v_add_f32_e32 v177, v106, v107
	v_add_f32_e32 v176, v176, v177
	v_add_f32_e32 v178, v108, v109
	v_add_f32_e32 v179, v110, v111
	v_add_f32_e32 v178, v178, v179
	v_add_f32_e32 v180, v112, v113
	v_add_f32_e32 v181, v114, v115
	v_add_f32_e32 v180, v180, v181
	v_add_f32_e32 v182, v116, v117
	v_add_f32_e32 v183, v118, v119
	v_add_f32_e32 v182, v182, v183
	ds_swizzle_b32 v169, v168 offset:swizzle(SWAP,16)
	ds_swizzle_b32 v171, v170 offset:swizzle(SWAP,16)
	ds_swizzle_b32 v173, v172 offset:swizzle(SWAP,16)
	ds_swizzle_b32 v175, v174 offset:swizzle(SWAP,16)
	ds_swizzle_b32 v177, v176 offset:swizzle(SWAP,16)
	ds_swizzle_b32 v179, v178 offset:swizzle(SWAP,16)
	ds_swizzle_b32 v181, v180 offset:swizzle(SWAP,16)
	ds_swizzle_b32 v183, v182 offset:swizzle(SWAP,16)
	s_waitcnt lgkmcnt(0)
	v_add_f32_e32 v168, v168, v169
	v_add_f32_e32 v170, v170, v171
	v_add_f32_e32 v172, v172, v173
	v_add_f32_e32 v174, v174, v175
	v_add_f32_e32 v176, v176, v177
	v_add_f32_e32 v178, v178, v179
	v_add_f32_e32 v180, v180, v181
	v_add_f32_e32 v182, v182, v183
	v_mov_b32_e32 v169, v168
	v_mov_b32_e32 v171, v170
	v_mov_b32_e32 v173, v172
	v_mov_b32_e32 v175, v174
	v_mov_b32_e32 v177, v176
	v_mov_b32_e32 v179, v178
	v_mov_b32_e32 v181, v180
	v_mov_b32_e32 v183, v182
	s_nop 1
	v_permlane32_swap_b32_e32 v168, v169
	v_permlane32_swap_b32_e32 v170, v171
	v_permlane32_swap_b32_e32 v172, v173
	v_permlane32_swap_b32_e32 v174, v175
	v_permlane32_swap_b32_e32 v176, v177
	v_permlane32_swap_b32_e32 v178, v179
	v_permlane32_swap_b32_e32 v180, v181
	v_permlane32_swap_b32_e32 v182, v183
	v_add_f32_e32 v168, v168, v169
	v_add_f32_e32 v170, v170, v171
	v_add_f32_e32 v172, v172, v173
	v_add_f32_e32 v174, v174, v175
	v_add_f32_e32 v176, v176, v177
	v_add_f32_e32 v178, v178, v179
	v_add_f32_e32 v180, v180, v181
	v_add_f32_e32 v182, v182, v183
	v_fmamk_f32 v168, v168, 0x3a800000, v246
	v_fmamk_f32 v170, v170, 0x3a800000, v246
	v_sqrt_f32_e32 v208, v168
	v_sqrt_f32_e32 v139, v170
	v_add_u32_e32 v209, -1, v208
	v_add_u32_e32 v140, -1, v139
	v_fma_f32 v210, -v209, v208, v168
	v_fma_f32 v141, -v140, v139, v170
	v_cmp_ge_f32_e64 s[98:99], 0, v210
	v_cmp_ge_f32_e64 s[16:17], 0, v141
	v_add_u32_e32 v210, 1, v208
	v_add_u32_e32 v141, 1, v139
	v_cndmask_b32_e64 v209, v208, v209, s[98:99]
	v_cndmask_b32_e64 v140, v139, v140, s[16:17]
	v_fma_f32 v211, -v210, v208, v168
	v_fma_f32 v142, -v141, v139, v170
	v_cmp_lt_f32_e64 s[98:99], 0, v211
	v_cmp_lt_f32_e64 s[16:17], 0, v142
	s_nop 0
	v_cndmask_b32_e64 v208, v209, v210, s[98:99]
	v_cndmask_b32_e64 v139, v140, v141, s[16:17]
	v_rcp_f32_e32 v209, v208
	v_rcp_f32_e32 v140, v139
	v_fma_f32 v210, -v208, v209, 1.0
	v_fma_f32 v141, -v139, v140, 1.0
	v_fmac_f32_e32 v209, v210, v209
	v_fmac_f32_e32 v140, v141, v140
	v_fma_f32 v212, -v208, v209, 1.0
	v_fma_f32 v143, -v139, v140, 1.0
	v_fma_f32 v211, v212, v209, v209
	v_fma_f32 v142, v143, v140, v140
	v_fma_f32 v212, -v208, v211, 1.0
	v_fma_f32 v143, -v139, v142, 1.0
	v_fma_f32 v168, v212, v209, v211
	v_fma_f32 v170, v143, v140, v142
	v_fmamk_f32 v172, v172, 0x3a800000, v246
	v_fmamk_f32 v174, v174, 0x3a800000, v246
	v_sqrt_f32_e32 v208, v172
	v_sqrt_f32_e32 v139, v174
	v_add_u32_e32 v209, -1, v208
	v_add_u32_e32 v140, -1, v139
	v_fma_f32 v210, -v209, v208, v172
	v_fma_f32 v141, -v140, v139, v174
	v_cmp_ge_f32_e64 s[98:99], 0, v210
	v_cmp_ge_f32_e64 s[16:17], 0, v141
	v_add_u32_e32 v210, 1, v208
	v_add_u32_e32 v141, 1, v139
	v_cndmask_b32_e64 v209, v208, v209, s[98:99]
	v_cndmask_b32_e64 v140, v139, v140, s[16:17]
	v_fma_f32 v211, -v210, v208, v172
	v_fma_f32 v142, -v141, v139, v174
	v_cmp_lt_f32_e64 s[98:99], 0, v211
	v_cmp_lt_f32_e64 s[16:17], 0, v142
	s_nop 0
	v_cndmask_b32_e64 v208, v209, v210, s[98:99]
	v_cndmask_b32_e64 v139, v140, v141, s[16:17]
	v_rcp_f32_e32 v209, v208
	v_rcp_f32_e32 v140, v139
	v_fma_f32 v210, -v208, v209, 1.0
	v_fma_f32 v141, -v139, v140, 1.0
	v_fmac_f32_e32 v209, v210, v209
	v_fmac_f32_e32 v140, v141, v140
	v_fma_f32 v212, -v208, v209, 1.0
	v_fma_f32 v143, -v139, v140, 1.0
; __device__ __forceinline__ unsigned cvt_pk_bf16(float lo, float hi) { unsigned r; asm volatile("v_cvt_pk_bf16_f32 %0, %1, %2" : "=v"(r) : "v"(lo), "v"(hi)); return r; }
; #define GAS __attribute__((address_space(1)))
;     DI void operator()(AccRef acc, const pg8::Unit& u, int wr, int wc, int, int) const {
;     ...
;                 { const float rsk = (kind == 4) ? rs * -1.4426950408889634f : rs; v0 = v0 * rsk; v1 = v1 * rsk; }
;     ...
;                 u32x4 w; w.x = cvt_pk_bf16(v0[0], v0[1]); w.y = cvt_pk_bf16(v0[2], v0[3]); w.z = cvt_pk_bf16(v1[0], v1[1]); w.w = cvt_pk_bf16(v1[2], v1[3]);
;                 *(GAS u32x4*)(dummy ? dummy + lane_ * 8 : Z + (size_t)lrow * ldz + col) = w;
	v_fma_f32 v211, v212, v209, v209
	v_fma_f32 v142, v143, v140, v140
	v_fma_f32 v212, -v208, v211, 1.0
	v_fma_f32 v143, -v139, v142, 1.0
	v_fma_f32 v172, v212, v209, v211
	v_fma_f32 v174, v143, v140, v142
	v_fmamk_f32 v176, v176, 0x3a800000, v246
	v_fmamk_f32 v178, v178, 0x3a800000, v246
	v_sqrt_f32_e32 v208, v176
	v_sqrt_f32_e32 v139, v178
	v_add_u32_e32 v209, -1, v208
	v_add_u32_e32 v140, -1, v139
	v_fma_f32 v210, -v209, v208, v176
	v_fma_f32 v141, -v140, v139, v178
	v_cmp_ge_f32_e64 s[98:99], 0, v210
	v_cmp_ge_f32_e64 s[16:17], 0, v141
	v_add_u32_e32 v210, 1, v208
	v_add_u32_e32 v141, 1, v139
	v_cndmask_b32_e64 v209, v208, v209, s[98:99]
	v_cndmask_b32_e64 v140, v139, v140, s[16:17]
	v_fma_f32 v211, -v210, v208, v176
	v_fma_f32 v142, -v141, v139, v178
	v_cmp_lt_f32_e64 s[98:99], 0, v211
	v_cmp_lt_f32_e64 s[16:17], 0, v142
	s_nop 0
	v_cndmask_b32_e64 v208, v209, v210, s[98:99]
	v_cndmask_b32_e64 v139, v140, v141, s[16:17]
	v_rcp_f32_e32 v209, v208
	v_rcp_f32_e32 v140, v139
	v_fma_f32 v210, -v208, v209, 1.0
	v_fma_f32 v141, -v139, v140, 1.0
	v_fmac_f32_e32 v209, v210, v209
	v_fmac_f32_e32 v140, v141, v140
	v_fma_f32 v212, -v208, v209, 1.0
	v_fma_f32 v143, -v139, v140, 1.0
	v_fma_f32 v211, v212, v209, v209
	v_fma_f32 v142, v143, v140, v140
	v_fma_f32 v212, -v208, v211, 1.0
	v_fma_f32 v143, -v139, v142, 1.0
	v_fma_f32 v176, v212, v209, v211
	v_fma_f32 v178, v143, v140, v142
	v_fmamk_f32 v180, v180, 0x3a800000, v246
	v_fmamk_f32 v182, v182, 0x3a800000, v246
	v_sqrt_f32_e32 v208, v180
	v_sqrt_f32_e32 v139, v182
	v_add_u32_e32 v209, -1, v208
	v_add_u32_e32 v140, -1, v139
	v_fma_f32 v210, -v209, v208, v180
	v_fma_f32 v141, -v140, v139, v182
	v_cmp_ge_f32_e64 s[98:99], 0, v210
	v_cmp_ge_f32_e64 s[16:17], 0, v141
	v_add_u32_e32 v210, 1, v208
	v_add_u32_e32 v141, 1, v139
	v_cndmask_b32_e64 v209, v208, v209, s[98:99]
	v_cndmask_b32_e64 v140, v139, v140, s[16:17]
	v_fma_f32 v211, -v210, v208, v180
	v_fma_f32 v142, -v141, v139, v182
	v_cmp_lt_f32_e64 s[98:99], 0, v211
	v_cmp_lt_f32_e64 s[16:17], 0, v142
	s_nop 0
	v_cndmask_b32_e64 v208, v209, v210, s[98:99]
	v_cndmask_b32_e64 v139, v140, v141, s[16:17]
	v_rcp_f32_e32 v209, v208
	v_rcp_f32_e32 v140, v139
	v_fma_f32 v210, -v208, v209, 1.0
	v_fma_f32 v141, -v139, v140, 1.0
	v_fmac_f32_e32 v209, v210, v209
	v_fmac_f32_e32 v140, v141, v140
	v_fma_f32 v212, -v208, v209, 1.0
	v_fma_f32 v143, -v139, v140, 1.0
	v_fma_f32 v211, v212, v209, v209
	v_fma_f32 v142, v143, v140, v140
	v_fma_f32 v212, -v208, v211, 1.0
	v_fma_f32 v143, -v139, v142, 1.0
	v_fma_f32 v180, v212, v209, v211
	v_fma_f32 v182, v143, v140, v142
	s_cmp_eq_u32 s8, 4
	s_cbranch_scc1 .Llean_F_sig
	v_pk_mul_f32 v[188:189], v[188:189], v[168:169] op_sel_hi:[1,0]
	v_pk_mul_f32 v[190:191], v[190:191], v[168:169] op_sel_hi:[1,0]
	v_pk_mul_f32 v[184:185], v[184:185], v[168:169] op_sel_hi:[1,0]
	v_pk_mul_f32 v[186:187], v[186:187], v[168:169] op_sel_hi:[1,0]
	v_cvt_pk_bf16_f32 v216, v188, v189
	v_cvt_pk_bf16_f32 v217, v190, v191
	v_cvt_pk_bf16_f32 v218, v184, v185
	v_cvt_pk_bf16_f32 v219, v186, v187
	global_store_dwordx4 v[146:147], v[216:219], off
	v_pk_mul_f32 v[164:165], v[164:165], v[168:169] op_sel_hi:[1,0]
	v_pk_mul_f32 v[166:167], v[166:167], v[168:169] op_sel_hi:[1,0]
	v_pk_mul_f32 v[160:161], v[160:161], v[168:169] op_sel_hi:[1,0]
	v_pk_mul_f32 v[162:163], v[162:163], v[168:169] op_sel_hi:[1,0]
	v_cvt_pk_bf16_f32 v220, v164, v165
	v_cvt_pk_bf16_f32 v221, v166, v167
	v_cvt_pk_bf16_f32 v222, v160, v161
	v_cvt_pk_bf16_f32 v223, v162, v163
	global_store_dwordx4 v[146:147], v[220:223], off offset:256
	v_lshl_add_u64 v[150:151], v[146:147], 0, s[2:3]
	v_pk_mul_f32 v[156:157], v[156:157], v[170:171] op_sel_hi:[1,0]
	v_pk_mul_f32 v[158:159], v[158:159], v[170:171] op_sel_hi:[1,0]
	v_pk_mul_f32 v[152:153], v[152:153], v[170:171] op_sel_hi:[1,0]
	v_pk_mul_f32 v[154:155], v[154:155], v[170:171] op_sel_hi:[1,0]
	v_cvt_pk_bf16_f32 v224, v156, v157
	v_cvt_pk_bf16_f32 v225, v158, v159
	v_cvt_pk_bf16_f32 v226, v152, v153
	v_cvt_pk_bf16_f32 v227, v154, v155
	global_store_dwordx4 v[150:151], v[224:227], off
	v_pk_mul_f32 v[132:133], v[132:133], v[170:171] op_sel_hi:[1,0]
	v_pk_mul_f32 v[134:135], v[134:135], v[170:171] op_sel_hi:[1,0]
	v_pk_mul_f32 v[128:129], v[128:129], v[170:171] op_sel_hi:[1,0]
	v_pk_mul_f32 v[130:131], v[130:131], v[170:171] op_sel_hi:[1,0]
	v_cvt_pk_bf16_f32 v228, v132, v133
	v_cvt_pk_bf16_f32 v229, v134, v135
	v_cvt_pk_bf16_f32 v230, v128, v129
	v_cvt_pk_bf16_f32 v231, v130, v131
	global_store_dwordx4 v[150:151], v[228:231], off offset:256
	v_lshl_add_u64 v[146:147], v[150:151], 0, s[2:3]
	v_pk_mul_f32 v[124:125], v[124:125], v[172:173] op_sel_hi:[1,0]
	v_pk_mul_f32 v[126:127], v[126:127], v[172:173] op_sel_hi:[1,0]
	v_pk_mul_f32 v[120:121], v[120:121], v[172:173] op_sel_hi:[1,0]
	v_pk_mul_f32 v[122:123], v[122:123], v[172:173] op_sel_hi:[1,0]
	v_cvt_pk_bf16_f32 v216, v124, v125
	v_cvt_pk_bf16_f32 v217, v126, v127
	v_cvt_pk_bf16_f32 v218, v120, v121
	v_cvt_pk_bf16_f32 v219, v122, v123
	global_store_dwordx4 v[146:147], v[216:219], off
; __device__ __forceinline__ unsigned cvt_pk_bf16(float lo, float hi) { unsigned r; asm volatile("v_cvt_pk_bf16_f32 %0, %1, %2" : "=v"(r) : "v"(lo), "v"(hi)); return r; }
; #define GAS __attribute__((address_space(1)))
;     DI void operator()(AccRef acc, const pg8::Unit& u, int wr, int wc, int, int) const {
;     ...
;                 { const float rsk = (kind == 4) ? rs * -1.4426950408889634f : rs; v0 = v0 * rsk; v1 = v1 * rsk; }
;     ...
;                 u32x4 w; w.x = cvt_pk_bf16(v0[0], v0[1]); w.y = cvt_pk_bf16(v0[2], v0[3]); w.z = cvt_pk_bf16(v1[0], v1[1]); w.w = cvt_pk_bf16(v1[2], v1[3]);
;                 *(GAS u32x4*)(dummy ? dummy + lane_ * 8 : Z + (size_t)lrow * ldz + col) = w;
	v_pk_mul_f32 v[100:101], v[100:101], v[172:173] op_sel_hi:[1,0]
	v_pk_mul_f32 v[102:103], v[102:103], v[172:173] op_sel_hi:[1,0]
	v_pk_mul_f32 v[96:97], v[96:97], v[172:173] op_sel_hi:[1,0]
	v_pk_mul_f32 v[98:99], v[98:99], v[172:173] op_sel_hi:[1,0]
	v_cvt_pk_bf16_f32 v220, v100, v101
	v_cvt_pk_bf16_f32 v221, v102, v103
	v_cvt_pk_bf16_f32 v222, v96, v97
	v_cvt_pk_bf16_f32 v223, v98, v99
	global_store_dwordx4 v[146:147], v[220:223], off offset:256
	v_lshl_add_u64 v[150:151], v[146:147], 0, s[2:3]
	v_pk_mul_f32 v[92:93], v[92:93], v[174:175] op_sel_hi:[1,0]
	v_pk_mul_f32 v[94:95], v[94:95], v[174:175] op_sel_hi:[1,0]
	v_pk_mul_f32 v[88:89], v[88:89], v[174:175] op_sel_hi:[1,0]
	v_pk_mul_f32 v[90:91], v[90:91], v[174:175] op_sel_hi:[1,0]
	v_cvt_pk_bf16_f32 v224, v92, v93
	v_cvt_pk_bf16_f32 v225, v94, v95
	v_cvt_pk_bf16_f32 v226, v88, v89
	v_cvt_pk_bf16_f32 v227, v90, v91
	global_store_dwordx4 v[150:151], v[224:227], off
	v_pk_mul_f32 v[68:69], v[68:69], v[174:175] op_sel_hi:[1,0]
	v_pk_mul_f32 v[70:71], v[70:71], v[174:175] op_sel_hi:[1,0]
	v_pk_mul_f32 v[64:65], v[64:65], v[174:175] op_sel_hi:[1,0]
	v_pk_mul_f32 v[66:67], v[66:67], v[174:175] op_sel_hi:[1,0]
	v_cvt_pk_bf16_f32 v228, v68, v69
	v_cvt_pk_bf16_f32 v229, v70, v71
	v_cvt_pk_bf16_f32 v230, v64, v65
	v_cvt_pk_bf16_f32 v231, v66, v67
	global_store_dwordx4 v[150:151], v[228:231], off offset:256
	v_lshl_add_u64 v[146:147], v[150:151], 0, s[0:1]
	v_pk_mul_f32 v[60:61], v[60:61], v[176:177] op_sel_hi:[1,0]
	v_pk_mul_f32 v[62:63], v[62:63], v[176:177] op_sel_hi:[1,0]
	v_pk_mul_f32 v[56:57], v[56:57], v[176:177] op_sel_hi:[1,0]
	v_pk_mul_f32 v[58:59], v[58:59], v[176:177] op_sel_hi:[1,0]
	v_cvt_pk_bf16_f32 v216, v60, v61
	v_cvt_pk_bf16_f32 v217, v62, v63
	v_cvt_pk_bf16_f32 v218, v56, v57
	v_cvt_pk_bf16_f32 v219, v58, v59
	global_store_dwordx4 v[146:147], v[216:219], off
	v_pk_mul_f32 v[52:53], v[52:53], v[176:177] op_sel_hi:[1,0]
	v_pk_mul_f32 v[54:55], v[54:55], v[176:177] op_sel_hi:[1,0]
	v_pk_mul_f32 v[48:49], v[48:49], v[176:177] op_sel_hi:[1,0]
	v_pk_mul_f32 v[50:51], v[50:51], v[176:177] op_sel_hi:[1,0]
	v_cvt_pk_bf16_f32 v220, v52, v53
	v_cvt_pk_bf16_f32 v221, v54, v55
	v_cvt_pk_bf16_f32 v222, v48, v49
	v_cvt_pk_bf16_f32 v223, v50, v51
	global_store_dwordx4 v[146:147], v[220:223], off offset:256
	v_lshl_add_u64 v[150:151], v[146:147], 0, s[2:3]
	v_pk_mul_f32 v[44:45], v[44:45], v[178:179] op_sel_hi:[1,0]
	v_pk_mul_f32 v[46:47], v[46:47], v[178:179] op_sel_hi:[1,0]
	v_pk_mul_f32 v[40:41], v[40:41], v[178:179] op_sel_hi:[1,0]
	v_pk_mul_f32 v[42:43], v[42:43], v[178:179] op_sel_hi:[1,0]
	v_cvt_pk_bf16_f32 v224, v44, v45
	v_cvt_pk_bf16_f32 v225, v46, v47
	v_cvt_pk_bf16_f32 v226, v40, v41
	v_cvt_pk_bf16_f32 v227, v42, v43
	global_store_dwordx4 v[150:151], v[224:227], off
	v_pk_mul_f32 v[36:37], v[36:37], v[178:179] op_sel_hi:[1,0]
	v_pk_mul_f32 v[38:39], v[38:39], v[178:179] op_sel_hi:[1,0]
	v_pk_mul_f32 v[32:33], v[32:33], v[178:179] op_sel_hi:[1,0]
	v_pk_mul_f32 v[34:35], v[34:35], v[178:179] op_sel_hi:[1,0]
	v_cvt_pk_bf16_f32 v228, v36, v37
	v_cvt_pk_bf16_f32 v229, v38, v39
	v_cvt_pk_bf16_f32 v230, v32, v33
	v_cvt_pk_bf16_f32 v231, v34, v35
	global_store_dwordx4 v[150:151], v[228:231], off offset:256
	v_lshl_add_u64 v[146:147], v[150:151], 0, s[2:3]
	v_pk_mul_f32 v[28:29], v[28:29], v[180:181] op_sel_hi:[1,0]
	v_pk_mul_f32 v[30:31], v[30:31], v[180:181] op_sel_hi:[1,0]
	v_pk_mul_f32 v[24:25], v[24:25], v[180:181] op_sel_hi:[1,0]
	v_pk_mul_f32 v[26:27], v[26:27], v[180:181] op_sel_hi:[1,0]
	v_cvt_pk_bf16_f32 v216, v28, v29
	v_cvt_pk_bf16_f32 v217, v30, v31
	v_cvt_pk_bf16_f32 v218, v24, v25
	v_cvt_pk_bf16_f32 v219, v26, v27
	global_store_dwordx4 v[146:147], v[216:219], off
	v_pk_mul_f32 v[20:21], v[20:21], v[180:181] op_sel_hi:[1,0]
	v_pk_mul_f32 v[22:23], v[22:23], v[180:181] op_sel_hi:[1,0]
	v_pk_mul_f32 v[16:17], v[16:17], v[180:181] op_sel_hi:[1,0]
	v_pk_mul_f32 v[18:19], v[18:19], v[180:181] op_sel_hi:[1,0]
	v_cvt_pk_bf16_f32 v220, v20, v21
	v_cvt_pk_bf16_f32 v221, v22, v23
	v_cvt_pk_bf16_f32 v222, v16, v17
	v_cvt_pk_bf16_f32 v223, v18, v19
	global_store_dwordx4 v[146:147], v[220:223], off offset:256
	v_lshl_add_u64 v[150:151], v[146:147], 0, s[2:3]
	v_pk_mul_f32 v[12:13], v[12:13], v[182:183] op_sel_hi:[1,0]
	v_pk_mul_f32 v[14:15], v[14:15], v[182:183] op_sel_hi:[1,0]
	v_pk_mul_f32 v[8:9], v[8:9], v[182:183] op_sel_hi:[1,0]
	v_pk_mul_f32 v[10:11], v[10:11], v[182:183] op_sel_hi:[1,0]
	v_cvt_pk_bf16_f32 v224, v12, v13
	v_cvt_pk_bf16_f32 v225, v14, v15
	v_cvt_pk_bf16_f32 v226, v8, v9
	v_cvt_pk_bf16_f32 v227, v10, v11
	global_store_dwordx4 v[150:151], v[224:227], off
	v_pk_mul_f32 v[4:5], v[4:5], v[182:183] op_sel_hi:[1,0]
	v_pk_mul_f32 v[6:7], v[6:7], v[182:183] op_sel_hi:[1,0]
	v_pk_mul_f32 v[0:1], v[0:1], v[182:183] op_sel_hi:[1,0]
	v_pk_mul_f32 v[2:3], v[2:3], v[182:183] op_sel_hi:[1,0]
	v_cvt_pk_bf16_f32 v228, v4, v5
	v_cvt_pk_bf16_f32 v229, v6, v7
	v_cvt_pk_bf16_f32 v230, v0, v1
	v_cvt_pk_bf16_f32 v231, v2, v3
	global_store_dwordx4 v[150:151], v[228:231], off offset:256
	s_branch .Llean_F_exit
